# XCD-local fast barriers: L1 invalidate issued on entry (overlaps the arrive+poll) instead of after the wait
# speedup vs baseline: 1.0046x; 1.0006x over previous
.LBB0_164:
	s_waitcnt vmcnt(0)
	v_readfirstlane_b32 s0, v194
	s_cmp_gt_u32 s0, 63
	s_waitcnt vmcnt(0)
	s_barrier
	s_cbranch_scc1 .LBB0_218
	v_mbcnt_lo_u32_b32 v0, -1, 0
	v_mbcnt_hi_u32_b32 v0, -1, v0
	s_nop 0
	v_cmp_eq_u32_e32 vcc, 0, v0
	s_and_saveexec_b64 s[0:1], vcc
	s_cbranch_execz .LBB0_217
	v_mov_b32_e32 v0, 0x23ff0
	s_waitcnt vmcnt(0) lgkmcnt(0)
	ds_read_b128 v[0:3], v0
	s_waitcnt lgkmcnt(0)
	v_readfirstlane_b32 s3, v2
	s_nop 0
	s_cmp_eq_u32 s3, 0
	s_cbranch_scc1 .Lfb_slow_0
	buffer_inv sc1
	v_add_u32_e32 v3, 1, v3
	v_mov_b32_e32 v4, 0x23ffc
	ds_write_b32 v4, v3
	v_mul_lo_u32 v5, v3, v0
	s_getreg_b32 s3, hwreg(HW_REG_XCC_ID, 0, 4)
	s_and_b32 s3, s3, 7
	s_lshl_b32 s3, s3, 8
	s_add_u32 s3, s3, 0x3680
	s_add_u32 s4, s92, 0x510000
	s_addc_u32 s5, s93, 0
	v_mov_b32_e32 v6, s3
	v_mov_b32_e32 v7, 1
	global_atomic_add v6, v7, s[4:5]
	s_mov_b32 s8, 0

.Lfb_done_0:
	s_waitcnt vmcnt(0) lgkmcnt(0)
	s_branch .LBB0_217

.LBB0_308:
	s_waitcnt vmcnt(0)
	v_readfirstlane_b32 s4, v194
	s_cmp_gt_u32 s4, 63
	v_readlane_b32 s77, v242, 9
	v_readlane_b32 s78, v241, 13
	v_readlane_b32 s40, v241, 12
	v_readlane_b32 s41, v241, 4
	s_barrier
	s_cbranch_scc1 .LBB0_362
	v_mbcnt_lo_u32_b32 v0, -1, 0
	v_mbcnt_hi_u32_b32 v0, -1, v0
	s_nop 0
	v_cmp_eq_u32_e32 vcc, 0, v0
	s_and_saveexec_b64 s[6:7], vcc
	s_cbranch_execz .LBB0_361
	v_mov_b32_e32 v0, 0x23ff0
	s_waitcnt vmcnt(0) lgkmcnt(0)
	ds_read_b128 v[0:3], v0
	s_waitcnt lgkmcnt(0)
	v_readfirstlane_b32 s8, v2
	s_nop 0
	s_cmp_eq_u32 s8, 0
	s_cbranch_scc1 .Lfb_slow_1
	buffer_inv sc1
	v_add_u32_e32 v3, 1, v3
	v_mov_b32_e32 v4, 0x23ffc
	ds_write_b32 v4, v3
	v_mul_lo_u32 v5, v3, v0
	s_getreg_b32 s8, hwreg(HW_REG_XCC_ID, 0, 4)
	s_and_b32 s8, s8, 7
	s_lshl_b32 s8, s8, 8
	s_add_u32 s8, s8, 0x3680
	s_add_u32 s4, s92, 0x510000
	s_addc_u32 s5, s93, 0
	v_mov_b32_e32 v6, s8
	v_mov_b32_e32 v7, 1
	global_atomic_add v6, v7, s[4:5]
	s_mov_b32 s9, 0

.LBB0_689:
	s_waitcnt vmcnt(0)
	v_readfirstlane_b32 s3, v194
	s_cmp_gt_u32 s3, 63
	s_waitcnt lgkmcnt(0)
	s_barrier
	s_cbranch_scc1 .LBB0_743
	v_mbcnt_lo_u32_b32 v0, -1, 0
	v_mbcnt_hi_u32_b32 v0, -1, v0
	s_nop 0
	v_cmp_eq_u32_e32 vcc, 0, v0
	s_and_saveexec_b64 s[6:7], vcc
	s_cbranch_execz .LBB0_742
	v_mov_b32_e32 v20, 0x23ff0
	s_waitcnt vmcnt(0) lgkmcnt(0)
	ds_read_b128 v[20:23], v20
	s_waitcnt lgkmcnt(0)
	v_readfirstlane_b32 s3, v22
	s_nop 0
	s_cmp_eq_u32 s3, 0
	s_cbranch_scc1 .Lfb_slow_2
	buffer_inv sc1
	v_add_u32_e32 v23, 1, v23
	v_mov_b32_e32 v24, 0x23ffc
	ds_write_b32 v24, v23
	v_mul_lo_u32 v25, v23, v20
	s_getreg_b32 s3, hwreg(HW_REG_XCC_ID, 0, 4)
	s_and_b32 s3, s3, 7
	s_lshl_b32 s3, s3, 8
	s_add_u32 s3, s3, 0x3680
	s_add_u32 s4, s92, 0x510000
	s_addc_u32 s5, s93, 0
	v_mov_b32_e32 v26, s3
	v_mov_b32_e32 v27, 1
	global_atomic_add v26, v27, s[4:5]
	s_mov_b32 s8, 0

.LBB0_772:
	s_waitcnt vmcnt(0)
	v_readfirstlane_b32 s0, v194
	s_cmp_gt_u32 s0, 63
	s_waitcnt vmcnt(0)
	s_barrier
	s_cbranch_scc1 .LBB0_826
	v_mbcnt_lo_u32_b32 v0, -1, 0
	v_mbcnt_hi_u32_b32 v0, -1, v0
	s_nop 0
	v_cmp_eq_u32_e32 vcc, 0, v0
	s_and_saveexec_b64 s[0:1], vcc
	s_cbranch_execz .LBB0_825
	v_mov_b32_e32 v20, 0x23ff0
	s_waitcnt vmcnt(0) lgkmcnt(0)
	ds_read_b128 v[20:23], v20
	s_waitcnt lgkmcnt(0)
	v_readfirstlane_b32 s3, v22
	s_nop 0
	s_cmp_eq_u32 s3, 0
	s_cbranch_scc1 .Lfb_slow_3
	buffer_inv sc1
	v_add_u32_e32 v23, 1, v23
	v_mov_b32_e32 v24, 0x23ffc
	ds_write_b32 v24, v23
	v_mul_lo_u32 v25, v23, v20
	s_getreg_b32 s3, hwreg(HW_REG_XCC_ID, 0, 4)
	s_and_b32 s3, s3, 7
	s_lshl_b32 s3, s3, 8
	s_add_u32 s3, s3, 0x3680
	s_add_u32 s4, s92, 0x510000
	s_addc_u32 s5, s93, 0
	v_mov_b32_e32 v26, s3
	v_mov_b32_e32 v27, 1
	global_atomic_add v26, v27, s[4:5]
	s_mov_b32 s8, 0

.LBB0_1157:
	s_waitcnt vmcnt(0)
	v_readfirstlane_b32 s0, v194
	v_readlane_b32 s62, v241, 5
	s_cmp_gt_u32 s0, 63
	v_readlane_b32 s63, v241, 6
	s_waitcnt lgkmcnt(0)
	s_barrier
	s_cbranch_scc1 .LBB0_1211
	v_mbcnt_lo_u32_b32 v0, -1, 0
	v_mbcnt_hi_u32_b32 v0, -1, v0
	s_nop 0
	v_cmp_eq_u32_e32 vcc, 0, v0
	s_and_saveexec_b64 s[0:1], vcc
	s_cbranch_execz .LBB0_1210
	v_mov_b32_e32 v20, 0x23ff0
	s_waitcnt vmcnt(0) lgkmcnt(0)
	ds_read_b128 v[20:23], v20
	s_waitcnt lgkmcnt(0)
	v_readfirstlane_b32 s3, v22
	s_nop 0
	s_cmp_eq_u32 s3, 0
	s_cbranch_scc1 .Lfb_slow_6
	buffer_inv sc1
	v_add_u32_e32 v23, 1, v23
	v_mov_b32_e32 v24, 0x23ffc
	ds_write_b32 v24, v23
	v_mul_lo_u32 v25, v23, v20
	s_getreg_b32 s3, hwreg(HW_REG_XCC_ID, 0, 4)
	s_and_b32 s3, s3, 7
	s_lshl_b32 s3, s3, 8
	s_add_u32 s3, s3, 0x3680
	s_add_u32 s4, s92, 0x510000
	s_addc_u32 s5, s93, 0
	v_mov_b32_e32 v26, s3
	v_mov_b32_e32 v27, 1
	global_atomic_add v26, v27, s[4:5]
	s_mov_b32 s8, 0
